# G1 accumulator-init elision: peeled first K-block of each later tile uses srcC=0 on the first MFMA per accumulator, 128 v_mov zeroing skipped
# speedup vs baseline: 1.0039x; 1.0039x over previous
.LBB0_344:
	s_ashr_i32 s37, s36, 31
	v_cmp_lt_i64_e32 vcc, s[38:39], v[142:143]
	s_lshl_b64 s[38:39], s[36:37], 20
	s_add_u32 s38, s30, s38
	s_addc_u32 s39, s31, s39
	s_and_b64 s[40:41], vcc, exec
	s_cselect_b32 s37, s39, s45
	s_cselect_b32 s72, s38, s44
	s_ashr_i32 s27, s26, 31
	s_lshl_b64 s[40:41], s[26:27], 20
	s_add_u32 s40, s56, s40
	s_addc_u32 s41, s57, s41
	s_and_b64 s[50:51], vcc, exec
	s_cselect_b32 s27, s41, s47
	s_cselect_b32 s73, s40, s46
	s_add_u32 s44, s44, 0x80080
	s_addc_u32 s45, s45, 0
	s_add_u32 s74, s46, 0x100
	s_addc_u32 s75, s47, 0
	s_mov_b32 s76, -2
	s_cmp_lg_u32 s99, 0
	s_cbranch_scc1 .Lmy_zskip_g1
	v_mov_b32_e32 v2, 0
	v_mov_b32_e32 v3, v2
	v_mov_b32_e32 v4, v2
	v_mov_b32_e32 v5, v2
	v_mov_b32_e32 v6, v2
	v_mov_b32_e32 v7, v2
	v_mov_b32_e32 v8, v2
	v_mov_b32_e32 v9, v2
	v_mov_b32_e32 v10, v2
	v_mov_b32_e32 v11, v2
	v_mov_b32_e32 v12, v2
	v_mov_b32_e32 v13, v2
	v_mov_b32_e32 v18, v2
	v_mov_b32_e32 v19, v2
	v_mov_b32_e32 v20, v2
	v_mov_b32_e32 v21, v2
	v_mov_b32_e32 v26, v2
	v_mov_b32_e32 v27, v2
	v_mov_b32_e32 v28, v2
	v_mov_b32_e32 v29, v2
	v_mov_b32_e32 v34, v2
	v_mov_b32_e32 v35, v2
	v_mov_b32_e32 v36, v2
	v_mov_b32_e32 v37, v2
	v_mov_b32_e32 v42, v2
	v_mov_b32_e32 v43, v2
	v_mov_b32_e32 v44, v2
	v_mov_b32_e32 v45, v2
	v_mov_b32_e32 v50, v2
	v_mov_b32_e32 v51, v2
	v_mov_b32_e32 v52, v2
	v_mov_b32_e32 v53, v2
	v_mov_b32_e32 v14, v2
	v_mov_b32_e32 v15, v2
	v_mov_b32_e32 v16, v2
	v_mov_b32_e32 v17, v2
	v_mov_b32_e32 v22, v2
	v_mov_b32_e32 v23, v2
	v_mov_b32_e32 v24, v2
	v_mov_b32_e32 v25, v2
	v_mov_b32_e32 v30, v2
	v_mov_b32_e32 v31, v2
	v_mov_b32_e32 v32, v2
	v_mov_b32_e32 v33, v2
	v_mov_b32_e32 v38, v2
	v_mov_b32_e32 v39, v2
	v_mov_b32_e32 v40, v2
	v_mov_b32_e32 v41, v2
	v_mov_b32_e32 v46, v2
	v_mov_b32_e32 v47, v2
	v_mov_b32_e32 v48, v2
	v_mov_b32_e32 v49, v2
	v_mov_b32_e32 v54, v2
	v_mov_b32_e32 v55, v2
	v_mov_b32_e32 v56, v2
	v_mov_b32_e32 v57, v2
	v_mov_b32_e32 v58, v2
	v_mov_b32_e32 v59, v2
	v_mov_b32_e32 v60, v2
	v_mov_b32_e32 v61, v2
	v_mov_b32_e32 v62, v2
	v_mov_b32_e32 v63, v2
	v_mov_b32_e32 v64, v2
	v_mov_b32_e32 v65, v2
	v_mov_b32_e32 v66, v2
	v_mov_b32_e32 v67, v2
	v_mov_b32_e32 v68, v2
	v_mov_b32_e32 v69, v2
	v_mov_b32_e32 v70, v2
	v_mov_b32_e32 v71, v2
	v_mov_b32_e32 v72, v2
	v_mov_b32_e32 v73, v2
	v_mov_b32_e32 v78, v2
	v_mov_b32_e32 v79, v2
	v_mov_b32_e32 v80, v2
	v_mov_b32_e32 v81, v2
	v_mov_b32_e32 v86, v2
	v_mov_b32_e32 v87, v2
	v_mov_b32_e32 v88, v2
	v_mov_b32_e32 v89, v2
	v_mov_b32_e32 v94, v2
	v_mov_b32_e32 v95, v2
	v_mov_b32_e32 v96, v2
	v_mov_b32_e32 v97, v2
	v_mov_b32_e32 v102, v2
	v_mov_b32_e32 v103, v2
	v_mov_b32_e32 v104, v2
	v_mov_b32_e32 v105, v2
	v_mov_b32_e32 v110, v2
	v_mov_b32_e32 v111, v2
	v_mov_b32_e32 v112, v2
	v_mov_b32_e32 v113, v2
	v_mov_b32_e32 v118, v2
	v_mov_b32_e32 v119, v2
	v_mov_b32_e32 v120, v2
	v_mov_b32_e32 v121, v2
	v_mov_b32_e32 v74, v2
	v_mov_b32_e32 v75, v2
	v_mov_b32_e32 v76, v2
	v_mov_b32_e32 v77, v2
	v_mov_b32_e32 v82, v2
	v_mov_b32_e32 v83, v2
	v_mov_b32_e32 v84, v2
	v_mov_b32_e32 v85, v2
	v_mov_b32_e32 v90, v2
	v_mov_b32_e32 v91, v2
	v_mov_b32_e32 v92, v2
	v_mov_b32_e32 v93, v2
	v_mov_b32_e32 v98, v2
	v_mov_b32_e32 v99, v2
	v_mov_b32_e32 v100, v2
	v_mov_b32_e32 v101, v2
	v_mov_b32_e32 v106, v2
	v_mov_b32_e32 v107, v2
	v_mov_b32_e32 v108, v2
	v_mov_b32_e32 v109, v2
	v_mov_b32_e32 v114, v2
	v_mov_b32_e32 v115, v2
	v_mov_b32_e32 v116, v2
	v_mov_b32_e32 v117, v2
	v_mov_b32_e32 v122, v2
	v_mov_b32_e32 v123, v2
	v_mov_b32_e32 v124, v2
	v_mov_b32_e32 v125, v2
	v_mov_b32_e32 v126, v2
	v_mov_b32_e32 v127, v2
	v_mov_b32_e32 v128, v2
	v_mov_b32_e32 v129, v2
	s_branch .LBB0_345
.Lmy_zskip_g1:
	ds_read_b128 v[164:167], v160
	ds_read_b128 v[168:171], v160 offset:1024
	ds_read_b128 v[172:175], v160 offset:2048
	ds_read_b128 v[176:179], v160 offset:3072
	s_add_u32 s46, s44, 0xfff80080
	s_addc_u32 s47, s45, -1
	s_cmp_eq_u32 s76, 28
	s_cselect_b32 s51, s37, s47
	s_cselect_b32 s50, s72, s46
	s_cselect_b32 s47, s27, s75
	s_cselect_b32 s46, s73, s74
	v_lshl_add_u64 v[148:149], s[44:45], 0, v[138:139]
	s_add_i32 m0, s34, 0xc000
	ds_read_b128 v[180:183], v161
	ds_read_b128 v[184:187], v161 offset:1024
	ds_read_b128 v[188:191], v161 offset:2048
	ds_read_b128 v[192:195], v161 offset:3072
	ds_read_b128 v[196:199], v161 offset:4096
	ds_read_b128 v[204:207], v161 offset:5120
	ds_read_b128 v[208:211], v161 offset:6144
	ds_read_b128 v[212:215], v161 offset:7168
	v_lshl_add_u64 v[148:149], s[44:45], 0, v[140:141]
	s_add_i32 m0, s34, 0xe000
	s_nop 0
	s_waitcnt lgkmcnt(8)
	s_barrier
	s_waitcnt lgkmcnt(0)
	s_setprio 1
	s_waitcnt lgkmcnt(0)
	v_mfma_f32_16x16x32_bf16 v[126:129], v[164:167], v[180:183], 0
	v_mfma_f32_16x16x32_bf16 v[122:125], v[172:175], v[180:183], 0
	v_mfma_f32_16x16x32_bf16 v[114:117], v[164:167], v[188:191], 0
	v_mfma_f32_16x16x32_bf16 v[106:109], v[172:175], v[188:191], 0
	v_mfma_f32_16x16x32_bf16 v[98:101], v[164:167], v[196:199], 0
	v_mfma_f32_16x16x32_bf16 v[90:93], v[172:175], v[196:199], 0
	v_mfma_f32_16x16x32_bf16 v[82:85], v[164:167], v[208:211], 0
	v_mfma_f32_16x16x32_bf16 v[74:77], v[172:175], v[208:211], 0
	v_mfma_f32_16x16x32_bf16 v[126:129], v[168:171], v[184:187], v[126:129]
	v_mfma_f32_16x16x32_bf16 v[122:125], v[176:179], v[184:187], v[122:125]
	v_mfma_f32_16x16x32_bf16 v[114:117], v[168:171], v[192:195], v[114:117]
	v_mfma_f32_16x16x32_bf16 v[106:109], v[176:179], v[192:195], v[106:109]
	v_mfma_f32_16x16x32_bf16 v[98:101], v[168:171], v[204:207], v[98:101]
	v_mfma_f32_16x16x32_bf16 v[90:93], v[176:179], v[204:207], v[90:93]
	v_mfma_f32_16x16x32_bf16 v[82:85], v[168:171], v[212:215], v[82:85]
	v_mfma_f32_16x16x32_bf16 v[74:77], v[176:179], v[212:215], v[74:77]
	s_setprio 0
	s_barrier
	s_add_i32 s77, s65, s33
	v_lshl_add_u64 v[148:149], s[46:47], 0, v[132:133]
	s_mov_b32 m0, s77
	ds_read_b128 v[216:219], v162
	ds_read_b128 v[220:223], v162 offset:1024
	ds_read_b128 v[224:227], v162 offset:2048
	ds_read_b128 v[228:231], v162 offset:3072
	global_load_lds_dwordx4 v[148:149], off
	v_lshl_add_u64 v[232:233], s[46:47], 0, v[136:137]
	s_add_i32 m0, s77, 0x2000
	s_nop 0
	global_load_lds_dwordx4 v[232:233], off
	s_barrier
	s_waitcnt lgkmcnt(0)
	s_setprio 1
	s_waitcnt lgkmcnt(0)
	v_mfma_f32_16x16x32_bf16 v[118:121], v[216:219], v[180:183], 0
	v_mfma_f32_16x16x32_bf16 v[110:113], v[224:227], v[180:183], 0
	v_mfma_f32_16x16x32_bf16 v[102:105], v[216:219], v[188:191], 0
	v_mfma_f32_16x16x32_bf16 v[94:97], v[224:227], v[188:191], 0
	v_mfma_f32_16x16x32_bf16 v[86:89], v[216:219], v[196:199], 0
	v_mfma_f32_16x16x32_bf16 v[78:81], v[224:227], v[196:199], 0
	v_mfma_f32_16x16x32_bf16 v[70:73], v[216:219], v[208:211], 0
	v_mfma_f32_16x16x32_bf16 v[66:69], v[224:227], v[208:211], 0
	v_mfma_f32_16x16x32_bf16 v[118:121], v[220:223], v[184:187], v[118:121]
	v_mfma_f32_16x16x32_bf16 v[110:113], v[228:231], v[184:187], v[110:113]
	v_mfma_f32_16x16x32_bf16 v[102:105], v[220:223], v[192:195], v[102:105]
	v_mfma_f32_16x16x32_bf16 v[94:97], v[228:231], v[192:195], v[94:97]
	v_mfma_f32_16x16x32_bf16 v[86:89], v[220:223], v[204:207], v[86:89]
	v_mfma_f32_16x16x32_bf16 v[78:81], v[228:231], v[204:207], v[78:81]
	v_mfma_f32_16x16x32_bf16 v[70:73], v[220:223], v[212:215], v[70:73]
	v_mfma_f32_16x16x32_bf16 v[66:69], v[228:231], v[212:215], v[66:69]
	s_setprio 0
	s_mov_b32 m0, s34
	v_lshl_add_u64 v[234:235], s[50:51], 0, v[130:131]
	s_barrier
	ds_read_b128 v[180:183], v161 offset:16384
	ds_read_b128 v[184:187], v161 offset:17408
	ds_read_b128 v[188:191], v161 offset:18432
	ds_read_b128 v[192:195], v161 offset:19456
	ds_read_b128 v[196:199], v161 offset:20480
	ds_read_b128 v[204:207], v161 offset:21504
	ds_read_b128 v[208:211], v161 offset:22528
	ds_read_b128 v[212:215], v161 offset:23552
	global_load_lds_dwordx4 v[234:235], off
	v_lshl_add_u64 v[236:237], s[50:51], 0, v[134:135]
	s_mov_b32 m0, s35
	s_nop 0
	global_load_lds_dwordx4 v[236:237], off
	s_barrier
	s_waitcnt lgkmcnt(0)
	s_setprio 1
	s_waitcnt lgkmcnt(0)
	v_mfma_f32_16x16x32_bf16 v[62:65], v[164:167], v[180:183], 0
	v_mfma_f32_16x16x32_bf16 v[58:61], v[172:175], v[180:183], 0
	v_mfma_f32_16x16x32_bf16 v[54:57], v[164:167], v[188:191], 0
	v_mfma_f32_16x16x32_bf16 v[46:49], v[172:175], v[188:191], 0
	v_mfma_f32_16x16x32_bf16 v[38:41], v[164:167], v[196:199], 0
	v_mfma_f32_16x16x32_bf16 v[30:33], v[172:175], v[196:199], 0
	v_mfma_f32_16x16x32_bf16 v[22:25], v[164:167], v[208:211], 0
	v_mfma_f32_16x16x32_bf16 v[14:17], v[172:175], v[208:211], 0
	v_mfma_f32_16x16x32_bf16 v[62:65], v[168:171], v[184:187], v[62:65]
	v_mfma_f32_16x16x32_bf16 v[58:61], v[176:179], v[184:187], v[58:61]
	v_mfma_f32_16x16x32_bf16 v[54:57], v[168:171], v[192:195], v[54:57]
	v_mfma_f32_16x16x32_bf16 v[46:49], v[176:179], v[192:195], v[46:49]
	v_mfma_f32_16x16x32_bf16 v[38:41], v[168:171], v[204:207], v[38:41]
	v_mfma_f32_16x16x32_bf16 v[30:33], v[176:179], v[204:207], v[30:33]
	v_mfma_f32_16x16x32_bf16 v[22:25], v[168:171], v[212:215], v[22:25]
	v_mfma_f32_16x16x32_bf16 v[14:17], v[176:179], v[212:215], v[14:17]
	s_setprio 0
	s_barrier
	s_add_u32 s78, s46, 0x80000
	s_addc_u32 s79, s47, 0
	s_add_i32 s77, s66, s33
	v_lshl_add_u64 v[164:165], s[78:79], 0, v[132:133]
	s_mov_b32 m0, s77
	s_nop 0
	global_load_lds_dwordx4 v[164:165], off
	v_lshl_add_u64 v[164:165], s[78:79], 0, v[136:137]
	s_add_i32 m0, s77, 0x2000
	s_nop 0
	global_load_lds_dwordx4 v[164:165], off
	s_waitcnt vmcnt(22)
	s_barrier
	s_setprio 1
	v_mfma_f32_16x16x32_bf16 v[50:53], v[216:219], v[180:183], 0
	v_mfma_f32_16x16x32_bf16 v[42:45], v[224:227], v[180:183], 0
	v_mfma_f32_16x16x32_bf16 v[34:37], v[216:219], v[188:191], 0
	v_mfma_f32_16x16x32_bf16 v[26:29], v[224:227], v[188:191], 0
	v_mfma_f32_16x16x32_bf16 v[18:21], v[216:219], v[196:199], 0
	v_mfma_f32_16x16x32_bf16 v[10:13], v[224:227], v[196:199], 0
	v_mfma_f32_16x16x32_bf16 v[6:9], v[216:219], v[208:211], 0
	v_mfma_f32_16x16x32_bf16 v[2:5], v[224:227], v[208:211], 0
	v_mfma_f32_16x16x32_bf16 v[50:53], v[220:223], v[184:187], v[50:53]
	v_mfma_f32_16x16x32_bf16 v[42:45], v[228:231], v[184:187], v[42:45]
	v_mfma_f32_16x16x32_bf16 v[34:37], v[220:223], v[192:195], v[34:37]
	v_mfma_f32_16x16x32_bf16 v[26:29], v[228:231], v[192:195], v[26:29]
	v_mfma_f32_16x16x32_bf16 v[18:21], v[220:223], v[204:207], v[18:21]
	v_mfma_f32_16x16x32_bf16 v[10:13], v[228:231], v[204:207], v[10:13]
	v_mfma_f32_16x16x32_bf16 v[6:9], v[220:223], v[212:215], v[6:9]
	v_mfma_f32_16x16x32_bf16 v[2:5], v[228:231], v[212:215], v[2:5]
	s_setprio 0
	s_add_i32 s77, 0, 0x18000
	v_add_u32_e32 v163, s77, v158
	s_barrier
	s_branch .Ltb_mid_g1
